# attention: the peeled last-key-tile blocks (run by waves 6,7 at each unit end) get the same software-pipelined LDS fragment reads as the main loops (40 serialized read-wait-MFMA steps per block before
# speedup vs baseline: 1.0063x; 1.0023x over previous
; #define LAS __attribute__((address_space(3)))
; __device__ __forceinline__ void attn_unit(LAS unsigned char* lds, const bf16_t* Q, const bf16_t* KN, const bf16_t* KPE, const bf16_t* VT, bf16_t* Y, float* ssq_b, int b, int h, int qg) {
;     ...
;         if (j <= cw) {
;             const LAS unsigned char* kb = lds + (j & 1) * KV_BYTES; const LAS unsigned char* vb = kb + KS_BYTES;
;             f32x16 s0, s1;
; #pragma unroll
;             for (int i = 0; i < 16; ++i) { s0[i] = 0.f; s1[i] = 0.f; }
;             __builtin_amdgcn_s_setprio(1);
;             {
;                 bf16x8 a0n = *(const LAS bf16x8*)(kb + kbase0), a1n = *(const LAS bf16x8*)(kb + (kbase0 + 32u * 384u));
; #pragma unroll
;                 for (int ks = 0; ks < 12; ++ks) {
;                     const bf16x8 a0 = a0n, a1 = a1n;
;                     if (ks + 1 < 12) { const unsigned off = (kbase0 ^ (unsigned)(((2 * (ks + 1)) & 7) << 4)) + (unsigned)(((2 * (ks + 1)) & 24) << 4);
;                         a0n = *(const LAS bf16x8*)(kb + off); a1n = *(const LAS bf16x8*)(kb + (off + 32u * 384u)); }
;                     s0 = __builtin_amdgcn_mfma_f32_32x32x16_bf16(a0, qf[ks], s0, 0, 0, 0);
;                     s1 = __builtin_amdgcn_mfma_f32_32x32x16_bf16(a1, qf[ks], s1, 0, 0, 0);
;                 }
;             }
;             __builtin_amdgcn_s_setprio(0);
;             if (j == 0) {
; #pragma unroll
;                 for (int i = 0; i < 16; ++i) { if (i >= 8) s0[i] = -INFINITY; s1[i] = -INFINITY; }
;             }
;             float mx = s0[0];
; #pragma unroll
;             for (int i = 1; i < 16; ++i) mx = fmaxf(mx, s0[i]);
; #pragma unroll
;             for (int i = 0; i < 16; ++i) mx = fmaxf(mx, s1[i]);
;             mx = fmaxf(mx, __shfl_xor(mx, 32));
;             const bool upd = __builtin_amdgcn_ballot_w64(mx - mrun > 8.0f) != 0ull;
;             const float mn = upd ? fmaxf(mrun, mx) : mrun; const float alpha = upd ? fexp2(mrun - mn) : 1.0f; mrun = mn;
;             s0 = s0 - mn; s1 = s1 - mn;
; #pragma unroll
;             for (int i = 0; i < 16; ++i) { s0[i] = fexp2(s0[i]); s1[i] = fexp2(s1[i]); }
;             const f32x16 t16 = s0 + s1;
;             typedef float f32x8_ __attribute__((ext_vector_type(8)));
;             const f32x8_ t8 = __builtin_shufflevector(t16, t16, 0, 1, 2, 3, 4, 5, 6, 7) + __builtin_shufflevector(t16, t16, 8, 9, 10, 11, 12, 13, 14, 15);
.LBB0_674:
	s_cmp_ge_u32 s52, s65
	s_cbranch_scc1 .LBB0_678
	s_setprio 1
	v_add_u32_e32 v150, s8, v197
	v_add_u32_e32 v160, s8, v199
	v_add_u32_e32 v161, s8, v200
	v_add_u32_e32 v252, s8, v201
	ds_read_b128 v[218:221], v150
	ds_read_b128 v[222:225], v150 offset:12288
	ds_read_b128 v[226:229], v160
	ds_read_b128 v[230:233], v160 offset:12288
	ds_read_b128 v[244:247], v161
	ds_read_b128 v[248:251], v161 offset:12288
	s_waitcnt lgkmcnt(5)
	v_mfma_f32_32x32x16_bf16 v[80:95], v[218:221], v[140:143], 0
	ds_read_b128 v[218:221], v252
	s_waitcnt lgkmcnt(5)
	v_mfma_f32_32x32x16_bf16 v[64:79], v[222:225], v[140:143], 0
	ds_read_b128 v[222:225], v252 offset:12288
	s_waitcnt lgkmcnt(5)
	v_mfma_f32_32x32x16_bf16 v[80:95], v[226:229], v[136:139], v[80:95]
	ds_read_b128 v[226:229], v150 offset:128
	s_waitcnt lgkmcnt(5)
	v_mfma_f32_32x32x16_bf16 v[64:79], v[230:233], v[136:139], v[64:79]
	ds_read_b128 v[230:233], v150 offset:12416
	s_waitcnt lgkmcnt(5)
	v_mfma_f32_32x32x16_bf16 v[80:95], v[244:247], v[132:135], v[80:95]
	ds_read_b128 v[244:247], v160 offset:128
	s_waitcnt lgkmcnt(5)
	v_mfma_f32_32x32x16_bf16 v[64:79], v[248:251], v[132:135], v[64:79]
	ds_read_b128 v[248:251], v160 offset:12416
	s_waitcnt lgkmcnt(5)
	v_mfma_f32_32x32x16_bf16 v[80:95], v[218:221], v[128:131], v[80:95]
	ds_read_b128 v[218:221], v161 offset:128
	s_waitcnt lgkmcnt(5)
	v_mfma_f32_32x32x16_bf16 v[64:79], v[222:225], v[128:131], v[64:79]
	ds_read_b128 v[222:225], v161 offset:12416
	s_waitcnt lgkmcnt(5)
	v_mfma_f32_32x32x16_bf16 v[80:95], v[226:229], v[124:127], v[80:95]
	ds_read_b128 v[226:229], v252 offset:128
	s_waitcnt lgkmcnt(5)
	v_mfma_f32_32x32x16_bf16 v[64:79], v[230:233], v[124:127], v[64:79]
	ds_read_b128 v[230:233], v252 offset:12416
	s_waitcnt lgkmcnt(5)
	v_mfma_f32_32x32x16_bf16 v[80:95], v[244:247], v[120:123], v[80:95]
	ds_read_b128 v[244:247], v150 offset:256
	s_waitcnt lgkmcnt(5)
	v_mfma_f32_32x32x16_bf16 v[64:79], v[248:251], v[120:123], v[64:79]
	ds_read_b128 v[248:251], v150 offset:12544
	s_waitcnt lgkmcnt(5)
	v_mfma_f32_32x32x16_bf16 v[80:95], v[218:221], v[116:119], v[80:95]
	ds_read_b128 v[218:221], v160 offset:256
	s_waitcnt lgkmcnt(5)
	v_mfma_f32_32x32x16_bf16 v[64:79], v[222:225], v[116:119], v[64:79]
	ds_read_b128 v[222:225], v160 offset:12544
	s_waitcnt lgkmcnt(5)
	v_mfma_f32_32x32x16_bf16 v[80:95], v[226:229], v[112:115], v[80:95]
	ds_read_b128 v[226:229], v161 offset:256
	s_waitcnt lgkmcnt(5)
	v_mfma_f32_32x32x16_bf16 v[64:79], v[230:233], v[112:115], v[64:79]
	ds_read_b128 v[230:233], v161 offset:12544
	s_waitcnt lgkmcnt(5)
	v_mfma_f32_32x32x16_bf16 v[80:95], v[244:247], v[108:111], v[80:95]
	ds_read_b128 v[244:247], v252 offset:256
	s_waitcnt lgkmcnt(5)
	v_mfma_f32_32x32x16_bf16 v[64:79], v[248:251], v[108:111], v[64:79]
	ds_read_b128 v[248:251], v252 offset:12544
	s_waitcnt lgkmcnt(5)
	v_mfma_f32_32x32x16_bf16 v[80:95], v[218:221], v[104:107], v[80:95]
	s_waitcnt lgkmcnt(4)
	v_mfma_f32_32x32x16_bf16 v[64:79], v[222:225], v[104:107], v[64:79]
	s_waitcnt lgkmcnt(3)
	v_mfma_f32_32x32x16_bf16 v[80:95], v[226:229], v[100:103], v[80:95]
	s_waitcnt lgkmcnt(2)
	v_mfma_f32_32x32x16_bf16 v[64:79], v[230:233], v[100:103], v[64:79]
	s_waitcnt lgkmcnt(1)
	v_mfma_f32_32x32x16_bf16 v[80:95], v[244:247], v[96:99], v[80:95]
	s_waitcnt lgkmcnt(0)
	v_mfma_f32_32x32x16_bf16 v[64:79], v[248:251], v[96:99], v[64:79]
	s_setprio 0
	s_nop 8
	v_max_f32_e32 v96, v81, v81
	v_max_f32_e32 v97, v80, v80
	v_max_f32_e32 v96, v97, v96
	v_max3_f32 v96, v96, v82, v83
	v_max3_f32 v96, v96, v84, v85
	v_max3_f32 v96, v96, v86, v87
	v_max3_f32 v96, v96, v88, v89
	v_max3_f32 v96, v96, v90, v91
	v_max3_f32 v96, v96, v92, v93
	v_max3_f32 v96, v96, v94, v95
	v_max3_f32 v96, v96, v64, v65
	v_max3_f32 v96, v96, v66, v67
	v_max3_f32 v96, v96, v68, v69
	v_max3_f32 v96, v96, v70, v71
	v_max3_f32 v96, v96, v72, v73
	v_max3_f32 v96, v96, v74, v75
	v_max3_f32 v96, v96, v76, v77
	v_max3_f32 v96, v96, v78, v79
	ds_bpermute_b32 v97, v205, v96
	s_waitcnt lgkmcnt(0)
	v_max_f32_e32 v97, v97, v97
	v_max_f32_e32 v96, v96, v97
	v_sub_f32_e32 v97, v96, v159
	v_cmp_lt_f32_e32 vcc, s38, v97
	s_cmp_eq_u64 vcc, 0
	v_max_f32_e32 v97, v159, v159
	s_cselect_b64 s[52:53], -1, 0
	v_max_f32_e32 v96, v97, v96
	v_cndmask_b32_e64 v97, v96, v159, s[52:53]
	v_sub_f32_e32 v96, v159, v97
	v_exp_f32_e32 v96, v96
	s_and_b64 vcc, exec, s[52:53]
	s_cbranch_vccnz .LBB0_677
	v_pk_mul_f32 v[62:63], v[62:63], v[96:97] op_sel_hi:[1,0]
	v_pk_mul_f32 v[60:61], v[60:61], v[96:97] op_sel_hi:[1,0]
	v_pk_mul_f32 v[58:59], v[58:59], v[96:97] op_sel_hi:[1,0]
	v_pk_mul_f32 v[56:57], v[56:57], v[96:97] op_sel_hi:[1,0]
	v_pk_mul_f32 v[54:55], v[54:55], v[96:97] op_sel_hi:[1,0]
	v_pk_mul_f32 v[52:53], v[52:53], v[96:97] op_sel_hi:[1,0]
	v_pk_mul_f32 v[50:51], v[50:51], v[96:97] op_sel_hi:[1,0]
	v_pk_mul_f32 v[48:49], v[48:49], v[96:97] op_sel_hi:[1,0]
	v_pk_mul_f32 v[46:47], v[46:47], v[96:97] op_sel_hi:[1,0]
	v_pk_mul_f32 v[44:45], v[44:45], v[96:97] op_sel_hi:[1,0]
	v_pk_mul_f32 v[42:43], v[42:43], v[96:97] op_sel_hi:[1,0]
	v_pk_mul_f32 v[40:41], v[40:41], v[96:97] op_sel_hi:[1,0]
	v_pk_mul_f32 v[38:39], v[38:39], v[96:97] op_sel_hi:[1,0]
	v_pk_mul_f32 v[36:37], v[36:37], v[96:97] op_sel_hi:[1,0]
	v_pk_mul_f32 v[34:35], v[34:35], v[96:97] op_sel_hi:[1,0]
	v_pk_mul_f32 v[32:33], v[32:33], v[96:97] op_sel_hi:[1,0]
	v_pk_mul_f32 v[30:31], v[30:31], v[96:97] op_sel_hi:[1,0]
	v_pk_mul_f32 v[28:29], v[28:29], v[96:97] op_sel_hi:[1,0]
	v_pk_mul_f32 v[26:27], v[26:27], v[96:97] op_sel_hi:[1,0]
	v_pk_mul_f32 v[24:25], v[24:25], v[96:97] op_sel_hi:[1,0]
	v_pk_mul_f32 v[22:23], v[22:23], v[96:97] op_sel_hi:[1,0]
	v_pk_mul_f32 v[20:21], v[20:21], v[96:97] op_sel_hi:[1,0]
	v_pk_mul_f32 v[18:19], v[18:19], v[96:97] op_sel_hi:[1,0]
	v_pk_mul_f32 v[16:17], v[16:17], v[96:97] op_sel_hi:[1,0]
	v_pk_mul_f32 v[14:15], v[14:15], v[96:97] op_sel_hi:[1,0]
	v_pk_mul_f32 v[12:13], v[12:13], v[96:97] op_sel_hi:[1,0]
	v_pk_mul_f32 v[10:11], v[10:11], v[96:97] op_sel_hi:[1,0]
	v_pk_mul_f32 v[8:9], v[8:9], v[96:97] op_sel_hi:[1,0]
	v_pk_mul_f32 v[6:7], v[6:7], v[96:97] op_sel_hi:[1,0]
	v_pk_mul_f32 v[4:5], v[4:5], v[96:97] op_sel_hi:[1,0]
	v_pk_mul_f32 v[2:3], v[2:3], v[96:97] op_sel_hi:[1,0]
	v_pk_mul_f32 v[0:1], v[0:1], v[96:97] op_sel_hi:[1,0]
; #define LAS __attribute__((address_space(3)))
; __device__ __forceinline__ void attn_unit(LAS unsigned char* lds, const bf16_t* Q, const bf16_t* KN, const bf16_t* KPE, const bf16_t* VT, bf16_t* Y, float* ssq_b, int b, int h, int qg) {
;     ...
;             const float mn = upd ? fmaxf(mrun, mx) : mrun; const float alpha = upd ? fexp2(mrun - mn) : 1.0f; mrun = mn;
;             s0 = s0 - mn; s1 = s1 - mn;
; #pragma unroll
;             for (int i = 0; i < 16; ++i) { s0[i] = fexp2(s0[i]); s1[i] = fexp2(s1[i]); }
;             const f32x16 t16 = s0 + s1;
;             typedef float f32x8_ __attribute__((ext_vector_type(8)));
;             const f32x8_ t8 = __builtin_shufflevector(t16, t16, 0, 1, 2, 3, 4, 5, 6, 7) + __builtin_shufflevector(t16, t16, 8, 9, 10, 11, 12, 13, 14, 15);
;             const f32x4 t4 = __builtin_shufflevector(t8, t8, 0, 1, 2, 3) + __builtin_shufflevector(t8, t8, 4, 5, 6, 7);
;             const float ps = (t4[0] + t4[1]) + (t4[2] + t4[3]);
;             lsum = lsum * alpha + ps;
;             if (upd) {
; #pragma unroll
;                 for (int d = 0; d < 4; ++d)
; #pragma unroll
;                     for (int i = 0; i < 16; ++i) o[d][i] *= alpha;
;             }
; #pragma unroll
;             for (int kb2 = 0; kb2 < 2; ++kb2)
; #pragma unroll
;                 for (int a = 0; a < 2; ++a) {
;                     u32x4 pw;
;                     if (kb2 == 0) { pw.x = cvt_pk(s0[8 * a + 0], s0[8 * a + 1]); pw.y = cvt_pk(s0[8 * a + 2], s0[8 * a + 3]); pw.z = cvt_pk(s0[8 * a + 4], s0[8 * a + 5]); pw.w = cvt_pk(s0[8 * a + 6], s0[8 * a + 7]); }
;                     else { pw.x = cvt_pk(s1[8 * a + 0], s1[8 * a + 1]); pw.y = cvt_pk(s1[8 * a + 2], s1[8 * a + 3]); pw.z = cvt_pk(s1[8 * a + 4], s1[8 * a + 5]); pw.w = cvt_pk(s1[8 * a + 6], s1[8 * a + 7]); }
;                     const bf16x8 pf = __builtin_bit_cast(bf16x8, pw);
;                     const unsigned vro = vbase0 ^ (unsigned)((4 * kb2 + 2 * a) << 4);
;                     __builtin_amdgcn_s_setprio(1);
; #pragma unroll
;                     for (int db = 0; db < 4; ++db) {
;                         const bf16x8 vf = *(const LAS bf16x8*)(vb + (vro + (unsigned)(db * 4096)));
;                         o[db] = __builtin_amdgcn_mfma_f32_32x32x16_bf16(vf, pf, o[db], 0, 0, 0);
;                     }
;                     __builtin_amdgcn_s_setprio(0);
;                 }
.LBB0_677:
	v_sub_f32_e32 v95, v95, v97
	v_sub_f32_e32 v94, v94, v97
	v_sub_f32_e32 v93, v93, v97
	v_sub_f32_e32 v92, v92, v97
	v_sub_f32_e32 v91, v91, v97
	v_sub_f32_e32 v90, v90, v97
	v_sub_f32_e32 v89, v89, v97
	v_sub_f32_e32 v88, v88, v97
	v_sub_f32_e32 v87, v87, v97
	v_sub_f32_e32 v86, v86, v97
	v_sub_f32_e32 v85, v85, v97
	v_sub_f32_e32 v84, v84, v97
	v_sub_f32_e32 v83, v83, v97
	v_sub_f32_e32 v82, v82, v97
	v_sub_f32_e32 v81, v81, v97
	v_sub_f32_e32 v80, v80, v97
	v_sub_f32_e32 v98, v79, v97
	v_sub_f32_e32 v99, v78, v97
	v_sub_f32_e32 v100, v77, v97
	v_sub_f32_e32 v101, v76, v97
	v_sub_f32_e32 v102, v75, v97
	v_sub_f32_e32 v103, v74, v97
	v_sub_f32_e32 v104, v73, v97
	v_sub_f32_e32 v105, v72, v97
	v_sub_f32_e32 v79, v71, v97
	v_sub_f32_e32 v71, v70, v97
	v_sub_f32_e32 v70, v69, v97
	v_sub_f32_e32 v69, v68, v97
	v_sub_f32_e32 v68, v67, v97
	v_sub_f32_e32 v67, v66, v97
	v_sub_f32_e32 v66, v65, v97
	v_sub_f32_e32 v65, v64, v97
	v_exp_f32_e32 v64, v80
	v_exp_f32_e32 v72, v65
	v_exp_f32_e32 v65, v81
	v_exp_f32_e32 v73, v66
	v_exp_f32_e32 v66, v82
	v_exp_f32_e32 v74, v67
	v_exp_f32_e32 v67, v83
	v_exp_f32_e32 v75, v68
	v_exp_f32_e32 v68, v84
	v_exp_f32_e32 v76, v69
	v_exp_f32_e32 v69, v85
	v_exp_f32_e32 v77, v70
	v_exp_f32_e32 v70, v86
	v_exp_f32_e32 v78, v71
	v_exp_f32_e32 v71, v87
	v_exp_f32_e32 v79, v79
	v_exp_f32_e32 v80, v88
	v_exp_f32_e32 v82, v105
	v_exp_f32_e32 v81, v89
	v_exp_f32_e32 v83, v104
	v_exp_f32_e32 v84, v90
	v_exp_f32_e32 v86, v103
	v_exp_f32_e32 v85, v91
	v_exp_f32_e32 v87, v102
	v_exp_f32_e32 v88, v92
	v_exp_f32_e32 v90, v101
	v_exp_f32_e32 v89, v93
	v_exp_f32_e32 v91, v100
	v_exp_f32_e32 v92, v94
	v_exp_f32_e32 v94, v99
	v_exp_f32_e32 v93, v95
	v_exp_f32_e32 v95, v98
	v_cndmask_b32_e64 v112, v96, 1.0, s[52:53]
	v_pk_add_f32 v[96:97], v[86:87], v[84:85]
	v_pk_add_f32 v[98:99], v[74:75], v[66:67]
	v_pk_add_f32 v[100:101], v[94:95], v[92:93]
	v_pk_add_f32 v[102:103], v[78:79], v[70:71]
	v_pk_add_f32 v[104:105], v[82:83], v[80:81]
	v_pk_add_f32 v[106:107], v[72:73], v[64:65]
	v_pk_add_f32 v[108:109], v[90:91], v[88:89]
	v_pk_add_f32 v[110:111], v[76:77], v[68:69]
	v_pk_add_f32 v[104:105], v[106:107], v[104:105]
	v_pk_add_f32 v[108:109], v[110:111], v[108:109]
	v_pk_add_f32 v[100:101], v[102:103], v[100:101]
	v_pk_add_f32 v[96:97], v[98:99], v[96:97]
	v_pk_add_f32 v[98:99], v[104:105], v[108:109]
	v_pk_add_f32 v[96:97], v[96:97], v[100:101]
	v_add_f32_e32 v98, v98, v99
	v_add_f32_e32 v96, v96, v97
	v_add_f32_e32 v96, v98, v96
	v_fmac_f32_e32 v96, v157, v112
	v_add_u32_e32 v252, s8, v198
	v_add_u32_e32 v253, s8, v202
	v_add_u32_e32 v254, s8, v203
	v_add_u32_e32 v255, s8, v204
	ds_read_b128 v[218:221], v252 offset:24576
	ds_read_b128 v[222:225], v252 offset:28672
	ds_read_b128 v[226:229], v252 offset:32768
	ds_read_b128 v[230:233], v252 offset:36864
	ds_read_b128 v[244:247], v253 offset:24576
	ds_read_b128 v[248:251], v253 offset:28672
	v_cvt_pk_bf16_f32 v64, v64, v65
	v_cvt_pk_bf16_f32 v65, v66, v67
	v_cvt_pk_bf16_f32 v66, v68, v69
	v_cvt_pk_bf16_f32 v67, v70, v71
	s_setprio 1
	s_waitcnt lgkmcnt(5)
	v_mfma_f32_32x32x16_bf16 v[48:63], v[218:221], v[64:67], v[48:63]
	ds_read_b128 v[218:221], v253 offset:32768
	s_waitcnt lgkmcnt(5)
	v_mfma_f32_32x32x16_bf16 v[32:47], v[222:225], v[64:67], v[32:47]
	ds_read_b128 v[222:225], v253 offset:36864
	s_waitcnt lgkmcnt(5)
	v_mfma_f32_32x32x16_bf16 v[16:31], v[226:229], v[64:67], v[16:31]
	ds_read_b128 v[226:229], v254 offset:24576
	s_waitcnt lgkmcnt(5)
	v_mfma_f32_32x32x16_bf16 v[0:15], v[230:233], v[64:67], v[0:15]
	ds_read_b128 v[230:233], v254 offset:28672
	s_setprio 0
	v_cvt_pk_bf16_f32 v64, v80, v81
	v_cvt_pk_bf16_f32 v65, v84, v85
	v_cvt_pk_bf16_f32 v66, v88, v89
	v_cvt_pk_bf16_f32 v67, v92, v93
	s_setprio 1
	s_waitcnt lgkmcnt(5)
	v_mfma_f32_32x32x16_bf16 v[48:63], v[244:247], v[64:67], v[48:63]
	ds_read_b128 v[244:247], v254 offset:32768
	s_waitcnt lgkmcnt(5)
	v_mfma_f32_32x32x16_bf16 v[32:47], v[248:251], v[64:67], v[32:47]
	ds_read_b128 v[248:251], v254 offset:36864
	s_waitcnt lgkmcnt(5)
	v_mfma_f32_32x32x16_bf16 v[16:31], v[218:221], v[64:67], v[16:31]
	ds_read_b128 v[218:221], v255 offset:24576
	s_waitcnt lgkmcnt(5)
	v_mfma_f32_32x32x16_bf16 v[0:15], v[222:225], v[64:67], v[0:15]
	ds_read_b128 v[222:225], v255 offset:28672
	s_setprio 0
	v_cvt_pk_bf16_f32 v64, v72, v73
	v_cvt_pk_bf16_f32 v65, v74, v75
	v_cvt_pk_bf16_f32 v66, v76, v77
	v_cvt_pk_bf16_f32 v67, v78, v79
	s_setprio 1
	s_waitcnt lgkmcnt(5)
	v_mfma_f32_32x32x16_bf16 v[48:63], v[226:229], v[64:67], v[48:63]
	ds_read_b128 v[226:229], v255 offset:32768
	s_waitcnt lgkmcnt(5)
	v_mfma_f32_32x32x16_bf16 v[32:47], v[230:233], v[64:67], v[32:47]
	ds_read_b128 v[230:233], v255 offset:36864
	s_waitcnt lgkmcnt(5)
	v_mfma_f32_32x32x16_bf16 v[16:31], v[244:247], v[64:67], v[16:31]
	s_waitcnt lgkmcnt(4)
	v_mfma_f32_32x32x16_bf16 v[0:15], v[248:251], v[64:67], v[0:15]
	s_setprio 0
	v_cvt_pk_bf16_f32 v64, v82, v83
	v_cvt_pk_bf16_f32 v65, v86, v87
	v_cvt_pk_bf16_f32 v66, v90, v91
	v_cvt_pk_bf16_f32 v67, v94, v95
	s_setprio 1
	s_waitcnt lgkmcnt(3)
	v_mfma_f32_32x32x16_bf16 v[48:63], v[218:221], v[64:67], v[48:63]
	s_waitcnt lgkmcnt(2)
	v_mfma_f32_32x32x16_bf16 v[32:47], v[222:225], v[64:67], v[32:47]
	s_waitcnt lgkmcnt(1)
	v_mfma_f32_32x32x16_bf16 v[16:31], v[226:229], v[64:67], v[16:31]
	s_waitcnt lgkmcnt(0)
	v_mfma_f32_32x32x16_bf16 v[0:15], v[230:233], v[64:67], v[0:15]
	s_setprio 0
	v_mov_b32_e32 v157, v96

; #define LAS __attribute__((address_space(3)))
; __device__ __forceinline__ void attn_unit(LAS unsigned char* lds, const bf16_t* Q, const bf16_t* KN, const bf16_t* KPE, const bf16_t* VT, bf16_t* Y, float* ssq_b, int b, int h, int qg) {
;     ...
;         if (j <= cw) {
;             const LAS unsigned char* kb = lds + (j & 1) * KV_BYTES; const LAS unsigned char* vb = kb + KS_BYTES;
;             f32x16 s0, s1;
; #pragma unroll
;             for (int i = 0; i < 16; ++i) { s0[i] = 0.f; s1[i] = 0.f; }
;             __builtin_amdgcn_s_setprio(1);
;             {
;                 bf16x8 a0n = *(const LAS bf16x8*)(kb + kbase0), a1n = *(const LAS bf16x8*)(kb + (kbase0 + 32u * 384u));
; #pragma unroll
;                 for (int ks = 0; ks < 12; ++ks) {
;                     const bf16x8 a0 = a0n, a1 = a1n;
;                     if (ks + 1 < 12) { const unsigned off = (kbase0 ^ (unsigned)(((2 * (ks + 1)) & 7) << 4)) + (unsigned)(((2 * (ks + 1)) & 24) << 4);
;                         a0n = *(const LAS bf16x8*)(kb + off); a1n = *(const LAS bf16x8*)(kb + (off + 32u * 384u)); }
;                     s0 = __builtin_amdgcn_mfma_f32_32x32x16_bf16(a0, qf[ks], s0, 0, 0, 0);
;                     s1 = __builtin_amdgcn_mfma_f32_32x32x16_bf16(a1, qf[ks], s1, 0, 0, 0);
;                 }
;             }
;             __builtin_amdgcn_s_setprio(0);
;             if (j == 0) {
; #pragma unroll
;                 for (int i = 0; i < 16; ++i) { if (i >= 8) s0[i] = -INFINITY; s1[i] = -INFINITY; }
;             }
;             float mx = s0[0];
; #pragma unroll
;             for (int i = 1; i < 16; ++i) mx = fmaxf(mx, s0[i]);
; #pragma unroll
;             for (int i = 0; i < 16; ++i) mx = fmaxf(mx, s1[i]);
;             mx = fmaxf(mx, __shfl_xor(mx, 32));
;             const bool upd = __builtin_amdgcn_ballot_w64(mx - mrun > 8.0f) != 0ull;
;             const float mn = upd ? fmaxf(mrun, mx) : mrun; const float alpha = upd ? fexp2(mrun - mn) : 1.0f; mrun = mn;
;             s0 = s0 - mn; s1 = s1 - mn;
; #pragma unroll
;             for (int i = 0; i < 16; ++i) { s0[i] = fexp2(s0[i]); s1[i] = fexp2(s1[i]); }
;             const f32x16 t16 = s0 + s1;
;             typedef float f32x8_ __attribute__((ext_vector_type(8)));
;             const f32x8_ t8 = __builtin_shufflevector(t16, t16, 0, 1, 2, 3, 4, 5, 6, 7) + __builtin_shufflevector(t16, t16, 8, 9, 10, 11, 12, 13, 14, 15);
.LBB0_702:
	s_cmp_ge_u32 s11, s10
	s_cbranch_scc1 .LBB0_706
	s_setprio 1
	v_add_u32_e32 v150, s6, v197
	v_add_u32_e32 v160, s6, v199
	v_add_u32_e32 v161, s6, v200
	v_add_u32_e32 v252, s6, v201
	ds_read_b128 v[208:211], v150
	ds_read_b128 v[214:217], v150 offset:12288
	ds_read_b128 v[218:221], v160
	ds_read_b128 v[222:225], v160 offset:12288
	ds_read_b128 v[244:247], v161
	ds_read_b128 v[248:251], v161 offset:12288
	s_waitcnt lgkmcnt(5)
	v_mfma_f32_32x32x16_bf16 v[80:95], v[208:211], v[140:143], 0
	ds_read_b128 v[208:211], v252
	s_waitcnt lgkmcnt(5)
	v_mfma_f32_32x32x16_bf16 v[64:79], v[214:217], v[140:143], 0
	ds_read_b128 v[214:217], v252 offset:12288
	s_waitcnt lgkmcnt(5)
	v_mfma_f32_32x32x16_bf16 v[80:95], v[218:221], v[136:139], v[80:95]
	ds_read_b128 v[218:221], v150 offset:128
	s_waitcnt lgkmcnt(5)
	v_mfma_f32_32x32x16_bf16 v[64:79], v[222:225], v[136:139], v[64:79]
	ds_read_b128 v[222:225], v150 offset:12416
	s_waitcnt lgkmcnt(5)
	v_mfma_f32_32x32x16_bf16 v[80:95], v[244:247], v[132:135], v[80:95]
	ds_read_b128 v[244:247], v160 offset:128
	s_waitcnt lgkmcnt(5)
	v_mfma_f32_32x32x16_bf16 v[64:79], v[248:251], v[132:135], v[64:79]
	ds_read_b128 v[248:251], v160 offset:12416
	s_waitcnt lgkmcnt(5)
	v_mfma_f32_32x32x16_bf16 v[80:95], v[208:211], v[128:131], v[80:95]
	ds_read_b128 v[208:211], v161 offset:128
	s_waitcnt lgkmcnt(5)
	v_mfma_f32_32x32x16_bf16 v[64:79], v[214:217], v[128:131], v[64:79]
	ds_read_b128 v[214:217], v161 offset:12416
	s_waitcnt lgkmcnt(5)
	v_mfma_f32_32x32x16_bf16 v[80:95], v[218:221], v[124:127], v[80:95]
	ds_read_b128 v[218:221], v252 offset:128
	s_waitcnt lgkmcnt(5)
	v_mfma_f32_32x32x16_bf16 v[64:79], v[222:225], v[124:127], v[64:79]
	ds_read_b128 v[222:225], v252 offset:12416
	s_waitcnt lgkmcnt(5)
	v_mfma_f32_32x32x16_bf16 v[80:95], v[244:247], v[120:123], v[80:95]
	ds_read_b128 v[244:247], v150 offset:256
	s_waitcnt lgkmcnt(5)
	v_mfma_f32_32x32x16_bf16 v[64:79], v[248:251], v[120:123], v[64:79]
	ds_read_b128 v[248:251], v150 offset:12544
	s_waitcnt lgkmcnt(5)
	v_mfma_f32_32x32x16_bf16 v[80:95], v[208:211], v[116:119], v[80:95]
	ds_read_b128 v[208:211], v160 offset:256
	s_waitcnt lgkmcnt(5)
	v_mfma_f32_32x32x16_bf16 v[64:79], v[214:217], v[116:119], v[64:79]
	ds_read_b128 v[214:217], v160 offset:12544
	s_waitcnt lgkmcnt(5)
	v_mfma_f32_32x32x16_bf16 v[80:95], v[218:221], v[112:115], v[80:95]
	ds_read_b128 v[218:221], v161 offset:256
	s_waitcnt lgkmcnt(5)
	v_mfma_f32_32x32x16_bf16 v[64:79], v[222:225], v[112:115], v[64:79]
	ds_read_b128 v[222:225], v161 offset:12544
	s_waitcnt lgkmcnt(5)
	v_mfma_f32_32x32x16_bf16 v[80:95], v[244:247], v[108:111], v[80:95]
	ds_read_b128 v[244:247], v252 offset:256
	s_waitcnt lgkmcnt(5)
	v_mfma_f32_32x32x16_bf16 v[64:79], v[248:251], v[108:111], v[64:79]
	ds_read_b128 v[248:251], v252 offset:12544
	s_waitcnt lgkmcnt(5)
	v_mfma_f32_32x32x16_bf16 v[80:95], v[208:211], v[104:107], v[80:95]
	s_waitcnt lgkmcnt(4)
	v_mfma_f32_32x32x16_bf16 v[64:79], v[214:217], v[104:107], v[64:79]
	s_waitcnt lgkmcnt(3)
	v_mfma_f32_32x32x16_bf16 v[80:95], v[218:221], v[100:103], v[80:95]
	s_waitcnt lgkmcnt(2)
	v_mfma_f32_32x32x16_bf16 v[64:79], v[222:225], v[100:103], v[64:79]
	s_waitcnt lgkmcnt(1)
	v_mfma_f32_32x32x16_bf16 v[80:95], v[244:247], v[96:99], v[80:95]
	s_waitcnt lgkmcnt(0)
	v_mfma_f32_32x32x16_bf16 v[64:79], v[248:251], v[96:99], v[64:79]
	s_setprio 0
	s_nop 8
	v_max_f32_e32 v96, v81, v81
	v_max_f32_e32 v97, v80, v80
	v_max_f32_e32 v96, v97, v96
	v_max3_f32 v96, v96, v82, v83
	v_max3_f32 v96, v96, v84, v85
	v_max3_f32 v96, v96, v86, v87
	v_max3_f32 v96, v96, v88, v89
	v_max3_f32 v96, v96, v90, v91
	v_max3_f32 v96, v96, v92, v93
	v_max3_f32 v96, v96, v94, v95
	v_max3_f32 v96, v96, v64, v65
	v_max3_f32 v96, v96, v66, v67
	v_max3_f32 v96, v96, v68, v69
	v_max3_f32 v96, v96, v70, v71
	v_max3_f32 v96, v96, v72, v73
	v_max3_f32 v96, v96, v74, v75
	v_max3_f32 v96, v96, v76, v77
	v_max3_f32 v96, v96, v78, v79
	ds_bpermute_b32 v97, v205, v96
	s_waitcnt lgkmcnt(0)
	v_max_f32_e32 v97, v97, v97
	v_max_f32_e32 v96, v96, v97
	v_sub_f32_e32 v97, v96, v159
	v_cmp_lt_f32_e32 vcc, s38, v97
	s_cmp_eq_u64 vcc, 0
	v_max_f32_e32 v97, v159, v159
	s_cselect_b64 s[52:53], -1, 0
	v_max_f32_e32 v96, v97, v96
	v_cndmask_b32_e64 v97, v96, v159, s[52:53]
	v_sub_f32_e32 v96, v159, v97
	v_exp_f32_e32 v96, v96
	s_and_b64 vcc, exec, s[52:53]
	s_cbranch_vccnz .LBB0_705
	v_pk_mul_f32 v[62:63], v[62:63], v[96:97] op_sel_hi:[1,0]
	v_pk_mul_f32 v[60:61], v[60:61], v[96:97] op_sel_hi:[1,0]
	v_pk_mul_f32 v[58:59], v[58:59], v[96:97] op_sel_hi:[1,0]
	v_pk_mul_f32 v[56:57], v[56:57], v[96:97] op_sel_hi:[1,0]
	v_pk_mul_f32 v[54:55], v[54:55], v[96:97] op_sel_hi:[1,0]
	v_pk_mul_f32 v[52:53], v[52:53], v[96:97] op_sel_hi:[1,0]
	v_pk_mul_f32 v[50:51], v[50:51], v[96:97] op_sel_hi:[1,0]
	v_pk_mul_f32 v[48:49], v[48:49], v[96:97] op_sel_hi:[1,0]
	v_pk_mul_f32 v[46:47], v[46:47], v[96:97] op_sel_hi:[1,0]
	v_pk_mul_f32 v[44:45], v[44:45], v[96:97] op_sel_hi:[1,0]
	v_pk_mul_f32 v[42:43], v[42:43], v[96:97] op_sel_hi:[1,0]
	v_pk_mul_f32 v[40:41], v[40:41], v[96:97] op_sel_hi:[1,0]
	v_pk_mul_f32 v[38:39], v[38:39], v[96:97] op_sel_hi:[1,0]
	v_pk_mul_f32 v[36:37], v[36:37], v[96:97] op_sel_hi:[1,0]
	v_pk_mul_f32 v[34:35], v[34:35], v[96:97] op_sel_hi:[1,0]
	v_pk_mul_f32 v[32:33], v[32:33], v[96:97] op_sel_hi:[1,0]
	v_pk_mul_f32 v[30:31], v[30:31], v[96:97] op_sel_hi:[1,0]
	v_pk_mul_f32 v[28:29], v[28:29], v[96:97] op_sel_hi:[1,0]
	v_pk_mul_f32 v[26:27], v[26:27], v[96:97] op_sel_hi:[1,0]
	v_pk_mul_f32 v[24:25], v[24:25], v[96:97] op_sel_hi:[1,0]
	v_pk_mul_f32 v[22:23], v[22:23], v[96:97] op_sel_hi:[1,0]
	v_pk_mul_f32 v[20:21], v[20:21], v[96:97] op_sel_hi:[1,0]
	v_pk_mul_f32 v[18:19], v[18:19], v[96:97] op_sel_hi:[1,0]
	v_pk_mul_f32 v[16:17], v[16:17], v[96:97] op_sel_hi:[1,0]
	v_pk_mul_f32 v[14:15], v[14:15], v[96:97] op_sel_hi:[1,0]
	v_pk_mul_f32 v[12:13], v[12:13], v[96:97] op_sel_hi:[1,0]
	v_pk_mul_f32 v[10:11], v[10:11], v[96:97] op_sel_hi:[1,0]
	v_pk_mul_f32 v[8:9], v[8:9], v[96:97] op_sel_hi:[1,0]
	v_pk_mul_f32 v[6:7], v[6:7], v[96:97] op_sel_hi:[1,0]
	v_pk_mul_f32 v[4:5], v[4:5], v[96:97] op_sel_hi:[1,0]
	v_pk_mul_f32 v[2:3], v[2:3], v[96:97] op_sel_hi:[1,0]
	v_pk_mul_f32 v[0:1], v[0:1], v[96:97] op_sel_hi:[1,0]
; #define LAS __attribute__((address_space(3)))
; __device__ __forceinline__ void attn_unit(LAS unsigned char* lds, const bf16_t* Q, const bf16_t* KN, const bf16_t* KPE, const bf16_t* VT, bf16_t* Y, float* ssq_b, int b, int h, int qg) {
;     ...
;             const float mn = upd ? fmaxf(mrun, mx) : mrun; const float alpha = upd ? fexp2(mrun - mn) : 1.0f; mrun = mn;
;             s0 = s0 - mn; s1 = s1 - mn;
; #pragma unroll
;             for (int i = 0; i < 16; ++i) { s0[i] = fexp2(s0[i]); s1[i] = fexp2(s1[i]); }
;             const f32x16 t16 = s0 + s1;
;             typedef float f32x8_ __attribute__((ext_vector_type(8)));
;             const f32x8_ t8 = __builtin_shufflevector(t16, t16, 0, 1, 2, 3, 4, 5, 6, 7) + __builtin_shufflevector(t16, t16, 8, 9, 10, 11, 12, 13, 14, 15);
;             const f32x4 t4 = __builtin_shufflevector(t8, t8, 0, 1, 2, 3) + __builtin_shufflevector(t8, t8, 4, 5, 6, 7);
;             const float ps = (t4[0] + t4[1]) + (t4[2] + t4[3]);
;             lsum = lsum * alpha + ps;
;             if (upd) {
; #pragma unroll
;                 for (int d = 0; d < 4; ++d)
; #pragma unroll
;                     for (int i = 0; i < 16; ++i) o[d][i] *= alpha;
;             }
; #pragma unroll
;             for (int kb2 = 0; kb2 < 2; ++kb2)
; #pragma unroll
;                 for (int a = 0; a < 2; ++a) {
;                     u32x4 pw;
;                     if (kb2 == 0) { pw.x = cvt_pk(s0[8 * a + 0], s0[8 * a + 1]); pw.y = cvt_pk(s0[8 * a + 2], s0[8 * a + 3]); pw.z = cvt_pk(s0[8 * a + 4], s0[8 * a + 5]); pw.w = cvt_pk(s0[8 * a + 6], s0[8 * a + 7]); }
;                     else { pw.x = cvt_pk(s1[8 * a + 0], s1[8 * a + 1]); pw.y = cvt_pk(s1[8 * a + 2], s1[8 * a + 3]); pw.z = cvt_pk(s1[8 * a + 4], s1[8 * a + 5]); pw.w = cvt_pk(s1[8 * a + 6], s1[8 * a + 7]); }
;                     const bf16x8 pf = __builtin_bit_cast(bf16x8, pw);
;                     const unsigned vro = vbase0 ^ (unsigned)((4 * kb2 + 2 * a) << 4);
;                     __builtin_amdgcn_s_setprio(1);
; #pragma unroll
;                     for (int db = 0; db < 4; ++db) {
;                         const bf16x8 vf = *(const LAS bf16x8*)(vb + (vro + (unsigned)(db * 4096)));
;                         o[db] = __builtin_amdgcn_mfma_f32_32x32x16_bf16(vf, pf, o[db], 0, 0, 0);
;                     }
;                     __builtin_amdgcn_s_setprio(0);
;                 }
.LBB0_705:
	v_sub_f32_e32 v95, v95, v97
	v_sub_f32_e32 v94, v94, v97
	v_sub_f32_e32 v93, v93, v97
	v_sub_f32_e32 v92, v92, v97
	v_sub_f32_e32 v91, v91, v97
	v_sub_f32_e32 v90, v90, v97
	v_sub_f32_e32 v89, v89, v97
	v_sub_f32_e32 v88, v88, v97
	v_sub_f32_e32 v87, v87, v97
	v_sub_f32_e32 v86, v86, v97
	v_sub_f32_e32 v85, v85, v97
	v_sub_f32_e32 v84, v84, v97
	v_sub_f32_e32 v83, v83, v97
	v_sub_f32_e32 v82, v82, v97
	v_sub_f32_e32 v81, v81, v97
	v_sub_f32_e32 v80, v80, v97
	v_sub_f32_e32 v98, v79, v97
	v_sub_f32_e32 v99, v78, v97
	v_sub_f32_e32 v100, v77, v97
	v_sub_f32_e32 v101, v76, v97
	v_sub_f32_e32 v102, v75, v97
	v_sub_f32_e32 v103, v74, v97
	v_sub_f32_e32 v104, v73, v97
	v_sub_f32_e32 v105, v72, v97
	v_sub_f32_e32 v79, v71, v97
	v_sub_f32_e32 v71, v70, v97
	v_sub_f32_e32 v70, v69, v97
	v_sub_f32_e32 v69, v68, v97
	v_sub_f32_e32 v68, v67, v97
	v_sub_f32_e32 v67, v66, v97
	v_sub_f32_e32 v66, v65, v97
	v_sub_f32_e32 v65, v64, v97
	v_exp_f32_e32 v64, v80
	v_exp_f32_e32 v72, v65
	v_exp_f32_e32 v65, v81
	v_exp_f32_e32 v73, v66
	v_exp_f32_e32 v66, v82
	v_exp_f32_e32 v74, v67
	v_exp_f32_e32 v67, v83
	v_exp_f32_e32 v75, v68
	v_exp_f32_e32 v68, v84
	v_exp_f32_e32 v76, v69
	v_exp_f32_e32 v69, v85
	v_exp_f32_e32 v77, v70
	v_exp_f32_e32 v70, v86
	v_exp_f32_e32 v78, v71
	v_exp_f32_e32 v71, v87
	v_exp_f32_e32 v79, v79
	v_exp_f32_e32 v80, v88
	v_exp_f32_e32 v82, v105
	v_exp_f32_e32 v81, v89
	v_exp_f32_e32 v83, v104
	v_exp_f32_e32 v84, v90
	v_exp_f32_e32 v86, v103
	v_exp_f32_e32 v85, v91
	v_exp_f32_e32 v87, v102
	v_exp_f32_e32 v88, v92
	v_exp_f32_e32 v90, v101
	v_exp_f32_e32 v89, v93
	v_exp_f32_e32 v91, v100
	v_exp_f32_e32 v92, v94
	v_exp_f32_e32 v94, v99
	v_exp_f32_e32 v93, v95
	v_exp_f32_e32 v95, v98
	v_cndmask_b32_e64 v112, v96, 1.0, s[52:53]
	v_pk_add_f32 v[96:97], v[86:87], v[84:85]
	v_pk_add_f32 v[98:99], v[74:75], v[66:67]
	v_pk_add_f32 v[100:101], v[94:95], v[92:93]
	v_pk_add_f32 v[102:103], v[78:79], v[70:71]
	v_pk_add_f32 v[104:105], v[82:83], v[80:81]
	v_pk_add_f32 v[106:107], v[72:73], v[64:65]
	v_pk_add_f32 v[108:109], v[90:91], v[88:89]
	v_pk_add_f32 v[110:111], v[76:77], v[68:69]
	v_pk_add_f32 v[104:105], v[106:107], v[104:105]
	v_pk_add_f32 v[108:109], v[110:111], v[108:109]
	v_pk_add_f32 v[100:101], v[102:103], v[100:101]
	v_pk_add_f32 v[96:97], v[98:99], v[96:97]
	v_pk_add_f32 v[98:99], v[104:105], v[108:109]
	v_pk_add_f32 v[96:97], v[96:97], v[100:101]
	v_add_f32_e32 v98, v98, v99
	v_add_f32_e32 v96, v96, v97
	v_add_f32_e32 v96, v98, v96
	v_fmac_f32_e32 v96, v157, v112
	v_add_u32_e32 v252, s6, v198
	v_add_u32_e32 v253, s6, v202
	v_add_u32_e32 v254, s6, v203
	v_add_u32_e32 v255, s6, v204
	ds_read_b128 v[208:211], v252 offset:24576
	ds_read_b128 v[214:217], v252 offset:28672
	ds_read_b128 v[218:221], v252 offset:32768
	ds_read_b128 v[222:225], v252 offset:36864
	ds_read_b128 v[244:247], v253 offset:24576
	ds_read_b128 v[248:251], v253 offset:28672
	v_cvt_pk_bf16_f32 v64, v64, v65
	v_cvt_pk_bf16_f32 v65, v66, v67
	v_cvt_pk_bf16_f32 v66, v68, v69
	v_cvt_pk_bf16_f32 v67, v70, v71
	s_setprio 1
	s_waitcnt lgkmcnt(5)
	v_mfma_f32_32x32x16_bf16 v[48:63], v[208:211], v[64:67], v[48:63]
	ds_read_b128 v[208:211], v253 offset:32768
	s_waitcnt lgkmcnt(5)
	v_mfma_f32_32x32x16_bf16 v[32:47], v[214:217], v[64:67], v[32:47]
	ds_read_b128 v[214:217], v253 offset:36864
	s_waitcnt lgkmcnt(5)
	v_mfma_f32_32x32x16_bf16 v[16:31], v[218:221], v[64:67], v[16:31]
	ds_read_b128 v[218:221], v254 offset:24576
	s_waitcnt lgkmcnt(5)
	v_mfma_f32_32x32x16_bf16 v[0:15], v[222:225], v[64:67], v[0:15]
	ds_read_b128 v[222:225], v254 offset:28672
	s_setprio 0
	v_cvt_pk_bf16_f32 v64, v80, v81
	v_cvt_pk_bf16_f32 v65, v84, v85
	v_cvt_pk_bf16_f32 v66, v88, v89
	v_cvt_pk_bf16_f32 v67, v92, v93
	s_setprio 1
	s_waitcnt lgkmcnt(5)
	v_mfma_f32_32x32x16_bf16 v[48:63], v[244:247], v[64:67], v[48:63]
	ds_read_b128 v[244:247], v254 offset:32768
	s_waitcnt lgkmcnt(5)
	v_mfma_f32_32x32x16_bf16 v[32:47], v[248:251], v[64:67], v[32:47]
	ds_read_b128 v[248:251], v254 offset:36864
	s_waitcnt lgkmcnt(5)
	v_mfma_f32_32x32x16_bf16 v[16:31], v[208:211], v[64:67], v[16:31]
	ds_read_b128 v[208:211], v255 offset:24576
	s_waitcnt lgkmcnt(5)
	v_mfma_f32_32x32x16_bf16 v[0:15], v[214:217], v[64:67], v[0:15]
	ds_read_b128 v[214:217], v255 offset:28672
	s_setprio 0
	v_cvt_pk_bf16_f32 v64, v72, v73
	v_cvt_pk_bf16_f32 v65, v74, v75
	v_cvt_pk_bf16_f32 v66, v76, v77
	v_cvt_pk_bf16_f32 v67, v78, v79
	s_setprio 1
	s_waitcnt lgkmcnt(5)
	v_mfma_f32_32x32x16_bf16 v[48:63], v[218:221], v[64:67], v[48:63]
	ds_read_b128 v[218:221], v255 offset:32768
	s_waitcnt lgkmcnt(5)
	v_mfma_f32_32x32x16_bf16 v[32:47], v[222:225], v[64:67], v[32:47]
	ds_read_b128 v[222:225], v255 offset:36864
	s_waitcnt lgkmcnt(5)
	v_mfma_f32_32x32x16_bf16 v[16:31], v[244:247], v[64:67], v[16:31]
	s_waitcnt lgkmcnt(4)
	v_mfma_f32_32x32x16_bf16 v[0:15], v[248:251], v[64:67], v[0:15]
	s_setprio 0
	v_cvt_pk_bf16_f32 v64, v82, v83
	v_cvt_pk_bf16_f32 v65, v86, v87
	v_cvt_pk_bf16_f32 v66, v90, v91
	v_cvt_pk_bf16_f32 v67, v94, v95
	s_setprio 1
	s_waitcnt lgkmcnt(3)
	v_mfma_f32_32x32x16_bf16 v[48:63], v[208:211], v[64:67], v[48:63]
	s_waitcnt lgkmcnt(2)
	v_mfma_f32_32x32x16_bf16 v[32:47], v[214:217], v[64:67], v[32:47]
	s_waitcnt lgkmcnt(1)
	v_mfma_f32_32x32x16_bf16 v[16:31], v[218:221], v[64:67], v[16:31]
	s_waitcnt lgkmcnt(0)
	v_mfma_f32_32x32x16_bf16 v[0:15], v[222:225], v[64:67], v[0:15]
	s_setprio 0
	v_mov_b32_e32 v157, v96
